# diff-attn loop v6: softmax-0 VALU interleaved into QK1 MFMA gaps (JIT fragments), softmax-1 in PV map-0 gaps; plus all previous phase patches
# speedup vs baseline: 1.0117x; 1.0117x over previous
; __device__ __forceinline__ int crow(int r, int hi) { return (r & 3) + 8 * (r >> 2) + 4 * hi; }
; template <int MODE, bool FAST>
; __device__ __forceinline__ int attn_item(const AttnP& a, int b, int h, int blk, char* lds) {
;     ...
;     const size_t bh = (size_t)(b * 8 + h);
;     const int qrow = 4 * blk + (wid >> 1), half = wid & 1;
;     const int qtok = MODE == 0 ? blk * 256 + wid * 32 : qrow * 64 + half * 32;
;     const int ulo = min(max(4 * blk - 4, 0), 116), r0w = min(max(qrow - 4, 0), 120);
;     {
;         const bf16_t* Qg = (MODE == 0 ? a.QA : a.QB) + (bh * SEQ + qtok) * 128;
; #pragma unroll
;         for (int i = 0; i < 8; ++i) { const int row = i * 4 + (lane >> 4), c16 = lane & 15;
;             const bf16x8 qv = *(const bf16x8*)(Qg + (size_t)row * 128 + c16 * 8);
;             *(bf16x8*)(Qw + KSWZ(row, c16 * 16)) = qv; }
;     }
;     const char* Kh = (const char*)((MODE == 0 ? a.KA : a.KB) + bh * SKV * 128);
;     const char* Vh = (const char*)((MODE == 0 ? a.VA : a.VB) + bh * SKV * 128);
;     unsigned voffK, voffV;
;     {
;         const int krow = 4 * wid + (lane >> 4), kch = (lane & 15) ^ (krow & 7);
;         voffK = (unsigned)(krow * 256 + kch * 16);
;         const int sub = 2 * wid + (lane >> 5), kk = (sub >> 2) * 8 + ((lane & 31) >> 2), cblk = sub & 3;
;         const int kreal = kk;
;         voffV = (unsigned)(kreal * 256 + (cblk * 32 + (lane & 3) * 8) * 2);
;     }
;     const int vb0 = (int)(uintptr_t)V_lds + v_rd_base(lane);
;     int koff[4];
; #pragma unroll
;     for (int i = 0; i < 4; ++i) koff[i] = r32 * 256 + (((2 * i + hi) ^ (r32 & 7)) << 4);
;     if (MODE == 1) { for (int i = tid; i < 768; i += 512) { const int k = i - 128; rpbz[i] = (k >= 0 && k < 465) ? a.rpb[h * 465 + k] * LOG2E : 0.f; } }
;     f32x16 negm0 = f32x16{}, negm1 = f32x16{};
;     if (MODE == 1 && FAST) { const int j = half * 32 + r32, c0 = min(max(j - 8, 0), 48);
; #pragma unroll
;         for (int r = 0; r < 16; ++r) { const int kc = crow(r, hi); negm0[r] = ((unsigned)(kc - c0) < 16u) ? 0.f : -1e30f; negm1[r] = ((unsigned)(kc + 32 - c0) < 16u) ? 0.f : -1e30f; } }
;     f32x16 o[NMAP][4]; float m_reg[NMAP], l_reg[NMAP];
; #pragma unroll
;     for (int mp = 0; mp < NMAP; ++mp) { m_reg[mp] = -1e30f; l_reg[mp] = 0.f;
; #pragma unroll
;         for (int d = 0; d < 4; ++d) o[mp][d] = f32x16{}; }
;     ...
;     STAGE(0, 0);
.LBB0_164:
	v_mov_b32_e32 v46, v200
	s_ashr_i32 s26, s61, 8
	v_readfirstlane_b32 s27, v46
	s_ashr_i32 s62, s27, 6
	s_lshl_b32 s4, s62, 13
	s_and_b32 s2, s61, 7
	s_add_i32 s4, s4, 0
	s_lshl_b32 s30, s26, 3
	s_and_b32 s6, s61, 0xf8
	s_add_i32 s31, s4, 0x11400
	s_or_b32 s4, s30, s2
	s_add_i32 s6, s62, s6
	s_ashr_i32 s5, s4, 31
	s_lshl_b32 s28, s6, 5
	s_and_b32 s7, s59, 7
	s_ashr_i32 s29, s28, 31
	s_lshl_b64 s[64:65], s[4:5], 21
	s_add_u32 s5, s38, s64
	s_addc_u32 s6, s39, s65
	s_lshl_b64 s[64:65], s[28:29], 8
	s_add_u32 s64, s5, s64
	v_bfe_u32 v47, v46, 4, 2
	v_and_b32_e32 v48, 15, v46
	s_addc_u32 s65, s6, s65
	v_lshlrev_b32_e32 v192, 4, v48
	v_or_b32_e32 v2, 4, v47
	v_lshl_add_u64 v[24:25], s[64:65], 0, v[192:193]
	v_lshlrev_b32_e32 v32, 8, v2
	v_mov_b32_e32 v33, v193
	v_lshlrev_b32_e32 v192, 8, v47
	v_lshl_add_u64 v[4:5], v[24:25], 0, v[32:33]
	v_or_b32_e32 v33, 12, v47
	v_or_b32_e32 v34, 0x800, v192
	v_mov_b32_e32 v35, v193
	v_lshlrev_b32_e32 v36, 8, v33
	v_mov_b32_e32 v37, v193
	v_lshl_add_u64 v[8:9], v[24:25], 0, v[34:35]
	v_lshl_add_u64 v[12:13], v[24:25], 0, v[36:37]
	v_or_b32_e32 v35, 20, v47
	v_or_b32_e32 v37, 28, v47
	v_or_b32_e32 v38, 0x1000, v192
	v_mov_b32_e32 v39, v193
	v_lshlrev_b32_e32 v40, 8, v35
	v_mov_b32_e32 v41, v193
	v_or_b32_e32 v42, 0x1800, v192
	v_mov_b32_e32 v43, v193
	v_lshlrev_b32_e32 v44, 8, v37
	v_mov_b32_e32 v45, v193
	v_lshl_add_u64 v[0:1], v[24:25], 0, v[192:193]
	v_lshl_add_u64 v[16:17], v[24:25], 0, v[38:39]
	v_lshl_add_u64 v[20:21], v[24:25], 0, v[40:41]
	v_lshl_add_u64 v[26:27], v[24:25], 0, v[42:43]
	v_lshl_add_u64 v[28:29], v[24:25], 0, v[44:45]
	global_load_dwordx4 v[0:3], v[0:1], off
	s_nop 0
	global_load_dwordx4 v[4:7], v[4:5], off
	s_nop 0
	global_load_dwordx4 v[8:11], v[8:9], off
	s_nop 0
	global_load_dwordx4 v[12:15], v[12:13], off
	s_nop 0
	global_load_dwordx4 v[16:19], v[16:17], off
	s_nop 0
	global_load_dwordx4 v[20:23], v[20:21], off
	s_nop 0
	global_load_dwordx4 v[24:27], v[26:27], off
	s_nop 0
	global_load_dwordx4 v[28:31], v[28:29], off
	v_bitop3_b32 v39, v47, v46, 15 bitop3:0x78
	v_bitop3_b32 v33, v33, v48, 7 bitop3:0x6c
	v_bitop3_b32 v37, v37, v48, 7 bitop3:0x6c
	v_bitop3_b32 v41, v47, v48, 4 bitop3:0x36
	v_lshlrev_b32_e32 v39, 4, v39
	v_bitop3_b32 v35, v35, v48, 7 bitop3:0x6c
	v_lshlrev_b32_e32 v33, 4, v33
	v_lshlrev_b32_e32 v37, 4, v37
	v_lshlrev_b32_e32 v41, 4, v41
	v_lshlrev_b32_e32 v35, 4, v35
	v_add3_u32 v33, s31, v36, v33
	v_add3_u32 v36, s31, v44, v37
	v_add3_u32 v37, s31, v192, v39
	v_and_b32_e32 v205, 31, v46
	v_bfe_u32 v204, v46, 5, 1
	v_add3_u32 v32, s31, v32, v41
	v_add3_u32 v35, s31, v40, v35
	s_lshl_b32 s5, s62, 1
	v_add3_u32 v34, s31, v34, v39
	v_add3_u32 v38, s31, v38, v39
	v_add3_u32 v39, s31, v42, v39
	s_ashr_i32 s63, s27, 4
	s_mul_i32 s64, s4, 0x210000
	s_mul_hi_i32 s6, s4, 0x210000
	s_add_u32 s4, s40, s64
	v_lshl_or_b32 v43, s62, 2, v47
	v_bitop3_b32 v45, v43, v48, 15 bitop3:0x6c
	v_lshlrev_b32_e32 v45, 4, v45
	v_and_b32_e32 v206, 63, v46
	v_mov_b32_e32 v40, v193
	v_mov_b32_e32 v41, v193
	v_mov_b32_e32 v42, v193
	v_mov_b32_e32 v44, v193
	v_mov_b32_e32 v47, v193
	v_mov_b32_e32 v48, 0
	v_mov_b32_e32 v49, v193
	v_mov_b32_e32 v50, v193
	v_mov_b32_e32 v51, v193
	v_mov_b32_e32 v52, v193
	v_mov_b32_e32 v53, v193
	s_waitcnt vmcnt(7)
	ds_write_b128 v37, v[0:3]
	s_waitcnt vmcnt(6)
	ds_write_b128 v32, v[4:7]
	s_waitcnt vmcnt(5)
	ds_write_b128 v34, v[8:11]
	s_waitcnt vmcnt(4)
	ds_write_b128 v33, v[12:15]
	s_waitcnt vmcnt(3)
	ds_write_b128 v38, v[16:19]
	s_waitcnt vmcnt(2)
	ds_write_b128 v35, v[20:23]
	s_waitcnt vmcnt(1)
	ds_write_b128 v39, v[24:27]
	s_waitcnt vmcnt(0)
	ds_write_b128 v36, v[28:31]
	v_lshlrev_b32_e32 v2, 1, v46
	v_and_b32_e32 v11, 32, v2
	v_lshlrev_b32_e32 v2, 8, v205
	v_and_b32_e32 v3, 7, v46
	v_bitop3_b32 v4, v204, v46, 7 bitop3:0x78
	v_and_or_b32 v0, s5, 2, v204
	v_lshl_or_b32 v207, v4, 4, v2
	v_bitop3_b32 v4, v204, v3, 2 bitop3:0x36
	s_addc_u32 s5, s41, s6
	s_and_b32 s65, s63, 0xfffff8
	v_bfe_u32 v8, v46, 2, 3
	v_lshl_or_b32 v208, v4, 4, v2
	v_bitop3_b32 v4, v204, v3, 4 bitop3:0x36
	v_bitop3_b32 v3, v204, v3, 6 bitop3:0x36
	s_add_u32 s64, s42, s64
	v_lshlrev_b32_e32 v1, 4, v46
	v_lshl_or_b32 v209, v4, 4, v2
	v_lshl_or_b32 v210, v3, 4, v2
	v_or_b32_e32 v2, s65, v8
	s_addc_u32 s65, s43, s6
	s_lshl_b32 s66, s62, 10
	v_lshlrev_b32_e32 v0, 6, v0
	v_and_b32_e32 v9, 48, v1
	v_lshlrev_b32_e32 v2, 8, v2
	s_add_i32 s6, s66, 0
	v_or3_b32 v0, v0, v9, v2
	v_lshl_or_b32 v2, v43, 8, v45
	v_mov_b32_e32 v3, v193
	s_add_i32 m0, s6, 0x8000
	v_and_b32_e32 v12, 0xc0, v1
	v_lshl_add_u64 v[4:5], s[4:5], 0, v[2:3]
	v_mov_b32_e32 v1, v193
	global_load_lds_dwordx4 v2, s[4:5]
	s_mov_b32 m0, s6
	v_lshl_add_u64 v[6:7], s[64:65], 0, v[0:1]
	global_load_lds_dwordx4 v0, s[64:65]
	v_lshl_add_u64 v[0:1], v[4:5], 0, s[16:17]
	s_add_i32 m0, s6, 0xa000
	v_lshlrev_b32_e32 v10, 3, v206
	global_load_lds_dwordx4 v[0:1], off
	v_lshl_add_u64 v[0:1], v[6:7], 0, s[16:17]
	s_add_i32 m0, s6, 0x2000
	s_cmp_lg_u32 0, -1
	global_load_lds_dwordx4 v[0:1], off
	v_and_b32_e32 v13, 24, v10
	s_cselect_b32 s4, 0, 0
	v_add3_u32 v1, v12, s4, v13
	s_or_b32 s4, s30, s7
	s_mul_hi_i32 s5, s4, 0x210000
	s_mul_i32 s4, s4, 0x210000
	s_add_u32 s4, s36, s4
	s_addc_u32 s5, s37, s5
	s_lshl_b32 s7, s63, 8
	s_waitcnt lgkmcnt(0)
; #define SBAR() __builtin_amdgcn_sched_barrier(0)
; template <int NMAP, int D0> __device__ __forceinline__ void pv_all(f32x16 (&o)[NMAP][4], int vb, const bf16x8 (&pa)[NMAP][4]) {
;     ...
;     for (int mp = 0; mp < NMAP; ++mp) o[mp][D0] = __builtin_amdgcn_mfma_f32_32x32x16_bf16(pa[mp][3], v3, o[mp][D0], 0, 0, 0);
; template <int MODE, bool FAST>
; __device__ __forceinline__ int attn_item(const AttnP& a, int b, int h, int blk, char* lds) {
;     ...
;     f32x16 o[NMAP][4]; float m_reg[NMAP], l_reg[NMAP];
; #pragma unroll
;     for (int mp = 0; mp < NMAP; ++mp) { m_reg[mp] = -1e30f; l_reg[mp] = 0.f;
; #pragma unroll
;         for (int d = 0; d < 4; ++d) o[mp][d] = f32x16{}; }
;     ...
;     STAGE(0, 0);
;     asm volatile("s_waitcnt lgkmcnt(0)" ::: "memory");
;     bf16x8 qreg[4];
; #pragma unroll
;     for (int i = 0; i < 4; ++i) qreg[i] = *(const bf16x8*)(Qw + koff[i]);
;     asm volatile("s_waitcnt vmcnt(0) lgkmcnt(0)" ::: "memory");
;     __syncthreads();
; #pragma nounroll
;     for (int t = 0; t < NT; ++t) {
;         const int cur = t & 1;
;         if (t + 1 < NT) STAGE(t + 1, cur ^ 1);
;         bool active = true; int br = 0;
;         if (MODE == 1 && t >= 4) { br = ulo + t - 4; active = (br >= r0w) && (br <= r0w + 7); }
;         if (active) {
;             const char* Kc = K_lds + cur * 16384; const int vb = vb0 + cur * 16384;
;             bf16x8 pa[NMAP][4];
; #pragma unroll
;             for (int mp = 0; mp < NMAP; ++mp) {
;                 SBAR();
;                 f32x16 p0 = f32x16{}, p1 = f32x16{};
;                 if (MODE == 1 && FAST && t >= 4) { p0 = negm0; p1 = negm1; }
; #pragma unroll
;                 for (int d0 = 0; d0 < KD0; ++d0) { const int dd = (MODE == 0 ? mp * 4 : 0) + d0; const int off = koff[dd & 3] + (dd >> 2) * 128;
;                     const bf16x8 k0 = *(const bf16x8*)(Kc + off); const bf16x8 k1 = *(const bf16x8*)(Kc + off + 8192);
	v_add_u32_e32 v211, s31, v207
	v_add_u32_e32 v213, s31, v209
	v_and_b32_e32 v0, 0x100, v10
	s_and_b32 s7, s7, 0xfffff800
	v_add_u32_e32 v212, s31, v208
	ds_read_b128 v[160:163], v211
	ds_read_b128 v[164:167], v212
	v_add_u32_e32 v214, s31, v210
	ds_read_b128 v[168:171], v213
	ds_read_b128 v[172:175], v214
	v_add3_u32 v215, v1, v11, v0
	v_lshl_or_b32 v0, v8, 8, s7
	s_lshl_b32 s7, s62, 7
	s_and_b32 s7, s7, 0x80
	s_waitcnt vmcnt(0) lgkmcnt(0)
	v_or3_b32 v192, s66, v192, v45
	v_or_b32_e32 v0, s7, v0
	v_lshlrev_b32_e32 v1, 6, v204
	v_lshl_add_u64 v[194:195], s[4:5], 0, v[192:193]
	v_or3_b32 v192, v0, v1, v9
	v_lshl_add_u64 v[196:197], s[4:5], 0, v[192:193]
	v_bfe_u32 v2, v205, 3, 1
	v_lshl_or_b32 v207, v2, 7, v207
	v_lshl_or_b32 v208, v2, 7, v208
	v_lshl_or_b32 v209, v2, 7, v209
	v_lshl_or_b32 v210, v2, 7, v210
	s_mov_b64 s[4:5], 0
	v_mov_b32_e32 v0, 0
	v_mov_b32_e32 v1, v193
	v_mov_b32_e32 v2, v193
	v_mov_b32_e32 v4, v193
	v_mov_b32_e32 v5, v193
	v_mov_b32_e32 v6, v193
	v_mov_b32_e32 v7, v193
	v_mov_b32_e32 v8, v193
	v_mov_b32_e32 v9, v193
	v_mov_b32_e32 v10, v193
	v_mov_b32_e32 v11, v193
	v_mov_b32_e32 v12, v193
	v_mov_b32_e32 v13, v193
	v_mov_b32_e32 v14, v193
	v_mov_b32_e32 v15, v193
	v_mov_b32_e32 v16, 0
	v_mov_b32_e32 v17, v193
	v_mov_b32_e32 v18, v193
	v_mov_b32_e32 v19, v193
	v_mov_b32_e32 v20, v193
	v_mov_b32_e32 v21, v193
	v_mov_b32_e32 v22, v193
	v_mov_b32_e32 v23, v193
	v_mov_b32_e32 v24, v193
	v_mov_b32_e32 v25, v193
	v_mov_b32_e32 v26, v193
	v_mov_b32_e32 v27, v193
	v_mov_b32_e32 v28, v193
	v_mov_b32_e32 v29, v193
	v_mov_b32_e32 v30, v193
	v_mov_b32_e32 v31, v193
	v_mov_b32_e32 v32, 0
	v_mov_b32_e32 v33, v193
	v_mov_b32_e32 v34, v193
	v_mov_b32_e32 v35, v193
	v_mov_b32_e32 v36, v193
	v_mov_b32_e32 v37, v193
	v_mov_b32_e32 v38, v193
	v_mov_b32_e32 v39, v193
	v_mov_b32_e32 v43, v193
	v_mov_b32_e32 v45, v193
	v_mov_b32_e32 v46, v193
	v_mov_b32_e32 v54, v193
	v_mov_b32_e32 v55, v193
	v_mov_b32_e32 v56, v193
	v_mov_b32_e32 v57, v193
	v_mov_b32_e32 v58, v193
	v_mov_b32_e32 v59, v193
	v_mov_b32_e32 v60, v193
	v_mov_b32_e32 v61, v193
	v_mov_b32_e32 v62, v193
	v_mov_b32_e32 v63, v193
	v_mov_b32_e32 v64, 0
	v_mov_b32_e32 v65, v193
	v_mov_b32_e32 v66, v193
	v_mov_b32_e32 v67, v193
	v_mov_b32_e32 v68, v193
	v_mov_b32_e32 v69, v193
	v_mov_b32_e32 v70, v193
	v_mov_b32_e32 v71, v193
	v_mov_b32_e32 v72, v193
	v_mov_b32_e32 v73, v193
	v_mov_b32_e32 v74, v193
	v_mov_b32_e32 v75, v193
	v_mov_b32_e32 v76, v193
	v_mov_b32_e32 v77, v193
	v_mov_b32_e32 v78, v193
	v_mov_b32_e32 v79, v193
	v_mov_b32_e32 v80, 0
	v_mov_b32_e32 v81, v193
	v_mov_b32_e32 v82, v193
	v_mov_b32_e32 v83, v193
	v_mov_b32_e32 v84, v193
	v_mov_b32_e32 v85, v193
	v_mov_b32_e32 v86, v193
	v_mov_b32_e32 v87, v193
	v_mov_b32_e32 v88, v193
	v_mov_b32_e32 v89, v193
	v_mov_b32_e32 v90, v193
	v_mov_b32_e32 v91, v193
	v_mov_b32_e32 v92, v193
	v_mov_b32_e32 v93, v193
	v_mov_b32_e32 v94, v193
	v_mov_b32_e32 v95, v193
	v_mov_b32_e32 v96, 0
	v_mov_b32_e32 v97, v193
	v_mov_b32_e32 v98, v193
	v_mov_b32_e32 v99, v193
	v_mov_b32_e32 v100, v193
	v_mov_b32_e32 v101, v193
	v_mov_b32_e32 v102, v193
	v_mov_b32_e32 v103, v193
	v_mov_b32_e32 v104, v193
	v_mov_b32_e32 v105, v193
	v_mov_b32_e32 v106, v193
	v_mov_b32_e32 v107, v193
	v_mov_b32_e32 v108, v193
	v_mov_b32_e32 v109, v193
	v_mov_b32_e32 v110, v193
	v_mov_b32_e32 v111, v193
	v_mov_b32_e32 v112, 0
	v_mov_b32_e32 v113, v193
	v_mov_b32_e32 v114, v193
	v_mov_b32_e32 v115, v193
	v_mov_b32_e32 v116, v193
	v_mov_b32_e32 v117, v193
	v_mov_b32_e32 v118, v193
	v_mov_b32_e32 v119, v193
	v_mov_b32_e32 v120, v193
	v_mov_b32_e32 v121, v193
	v_mov_b32_e32 v122, v193
	v_mov_b32_e32 v123, v193
	v_mov_b32_e32 v124, v193
	v_mov_b32_e32 v125, v193
	v_mov_b32_e32 v126, v193
	v_mov_b32_e32 v127, v193
	v_mov_b32_e32 v198, 0
	v_mov_b32_e32 v199, v193
	s_waitcnt vmcnt(0) lgkmcnt(0)
	s_barrier
	s_and_b32 s7, s4, 0x4000
	v_add_u32_e32 v252, s7, v207
	v_add_u32_e32 v253, s7, v208
	ds_read_b128 v[176:179], v252 offset:32768
	ds_read_b128 v[180:183], v252 offset:40960
	ds_read_b128 v[184:187], v253 offset:32768
	ds_read_b128 v[188:191], v253 offset:40960
	v_add_u32_e32 v252, s7, v209
	v_add_u32_e32 v253, s7, v210
	ds_read_b128 v[224:227], v252 offset:32768
	ds_read_b128 v[228:231], v252 offset:40960
	ds_read_b128 v[240:243], v253 offset:32768
	ds_read_b128 v[244:247], v253 offset:40960
	s_branch .Lmy_C
.Lmy_top:
	s_and_b32 s7, s4, 0x4000
	v_add_u32_e32 v252, s7, v207
	v_add_u32_e32 v253, s7, v208
	ds_read_b128 v[176:179], v252 offset:32768
	ds_read_b128 v[180:183], v252 offset:40960
	ds_read_b128 v[184:187], v253 offset:32768
	ds_read_b128 v[188:191], v253 offset:40960
	v_add_u32_e32 v252, s7, v209
	v_add_u32_e32 v253, s7, v210
	ds_read_b128 v[224:227], v252 offset:32768
	ds_read_b128 v[228:231], v252 offset:40960
	ds_read_b128 v[240:243], v253 offset:32768
	ds_read_b128 v[244:247], v253 offset:40960
	v_mfma_f32_32x32x16_bf16 v[112:127], v[216:219], v[136:139], v[112:127]
	v_mfma_f32_32x32x16_bf16 v[112:127], v[220:223], v[140:143], v[112:127]
	v_mfma_f32_32x32x16_bf16 v[112:127], v[232:235], v[152:155], v[112:127]
	v_mfma_f32_32x32x16_bf16 v[112:127], v[236:239], v[156:159], v[112:127]

; #define SBAR() __builtin_amdgcn_sched_barrier(0)
; __device__ __forceinline__ int crow(int r, int hi) { return (r & 3) + 8 * (r >> 2) + 4 * hi; }
; template <int MODE, bool FAST>
; __device__ __forceinline__ int attn_item(const AttnP& a, int b, int h, int blk, char* lds) {
;     ...
;                 for (int d0 = 0; d0 < KD0; ++d0) { const int dd = (MODE == 0 ? mp * 4 : 0) + d0; const int off = koff[dd & 3] + (dd >> 2) * 128;
;                     const bf16x8 k0 = *(const bf16x8*)(Kc + off); const bf16x8 k1 = *(const bf16x8*)(Kc + off + 8192);
;                     const bf16x8 qf = (dd < 4) ? qreg[dd < 4 ? dd : 0] : *(const bf16x8*)(Qw + off);
;                     p0 = __builtin_amdgcn_mfma_f32_32x32x16_bf16(k0, qf, p0, 0, 0, 0);
;                     p1 = __builtin_amdgcn_mfma_f32_32x32x16_bf16(k1, qf, p1, 0, 0, 0);
;                     if ((d0 & 1) == 1) SBAR(); }
;                 if (MODE == 1 && FAST && t >= 4) {
;                     const float* bp = rpbs + (br - qrow + 7) * 31 + 15 - (half * 32 + r32) + 4 * hi;
; #pragma unroll
;                     for (int r = 0; r < 16; ++r) { p0[r] += bp[(r & 3) + 8 * (r >> 2)]; p1[r] += bp[32 + (r & 3) + 8 * (r >> 2)]; }
;                 }
;                 if (MODE == 1 && !FAST && t >= 4) {
;                     const int j = half * 32 + r32, c0 = min(max(j - 8, 0), 48);
;                     const float* bp = rpbs + (br - qrow + 7) * 31 + 15 - j;
; #pragma unroll
;                     for (int r = 0; r < 16; ++r) { const int kc = crow(r, hi); const bool ok = (unsigned)(kc - c0) < 16u; const float bv = bp[ok ? kc : j];
;                         p0[r] = ok ? p0[r] + bv : -1e30f; }
; #pragma unroll
;                     for (int r = 0; r < 16; ++r) { const int kc = 32 + crow(r, hi); const bool ok = (unsigned)(kc - c0) < 16u; const float bv = bp[ok ? kc : j];
;                         p1[r] = ok ? p1[r] + bv : -1e30f; }
;                 }
;                 float alpha = 1.f;
;                 if (FAST) {
;                     float ps1 = 0.f;
; #pragma unroll
;                     for (int r = 0; r < 16; ++r) p0[r] = __builtin_amdgcn_exp2f(p0[r]);
; #pragma unroll
;                     for (int r = 0; r < 16; ++r) p1[r] = __builtin_amdgcn_exp2f(p1[r]);
; #pragma unroll
;                     for (int r = 0; r < 16; ++r) { ps1 += p0[r]; ps1 += p1[r]; }
;                     l_reg[mp] += ps1;
.Lmy_nopf:
	s_waitcnt lgkmcnt(6)
	v_mfma_f32_32x32x16_bf16 v[144:159], v[176:179], v[160:163], 0
	v_mfma_f32_32x32x16_bf16 v[128:143], v[180:183], v[160:163], 0
	s_waitcnt lgkmcnt(4)
	v_mfma_f32_32x32x16_bf16 v[144:159], v[184:187], v[164:167], v[144:159]
	v_mfma_f32_32x32x16_bf16 v[128:143], v[188:191], v[164:167], v[128:143]
	s_waitcnt lgkmcnt(2)
	v_mfma_f32_32x32x16_bf16 v[144:159], v[224:227], v[168:171], v[144:159]
	v_mfma_f32_32x32x16_bf16 v[128:143], v[228:231], v[168:171], v[128:143]
	s_waitcnt lgkmcnt(0)
	v_mfma_f32_32x32x16_bf16 v[144:159], v[240:243], v[172:175], v[144:159]
	v_mfma_f32_32x32x16_bf16 v[128:143], v[244:247], v[172:175], v[128:143]
	v_add_u32_e32 v192, s7, v207
	v_xor_b32_e32 v192, 0x80, v192
	v_add_u32_e32 v253, s7, v208
	v_xor_b32_e32 v253, 0x80, v253
	ds_read_b128 v[176:179], v211 offset:128
	ds_read_b128 v[180:183], v192 offset:32768
	ds_read_b128 v[184:187], v192 offset:40960
	ds_read_b128 v[188:191], v212 offset:128
	ds_read_b128 v[248:251], v253 offset:32768
	s_waitcnt lgkmcnt(3)
	v_mfma_f32_32x32x16_bf16 v[216:231], v[180:183], v[176:179], 0
	ds_read_b128 v[180:183], v253 offset:40960
	v_exp_f32_e32 v144, v144
	v_exp_f32_e32 v128, v128
	v_exp_f32_e32 v145, v145
	v_exp_f32_e32 v129, v129
	v_exp_f32_e32 v146, v146
	v_add_f32_e32 v252, 0, v144
	v_exp_f32_e32 v130, v130
	v_add_f32_e32 v252, v128, v252
	v_exp_f32_e32 v147, v147
	v_add_f32_e32 v252, v145, v252
	s_waitcnt lgkmcnt(3)
	v_mfma_f32_32x32x16_bf16 v[232:247], v[184:187], v[176:179], 0
	v_add_u32_e32 v192, s7, v209
	v_xor_b32_e32 v192, 0x80, v192
	ds_read_b128 v[176:179], v213 offset:128
	ds_read_b128 v[184:187], v192 offset:32768
	v_exp_f32_e32 v131, v131
	v_add_f32_e32 v252, v129, v252
	v_exp_f32_e32 v148, v148
	v_add_f32_e32 v252, v146, v252
	v_exp_f32_e32 v132, v132
	v_add_f32_e32 v252, v130, v252
	v_exp_f32_e32 v149, v149
	v_add_f32_e32 v252, v147, v252
	v_exp_f32_e32 v133, v133
	v_add_f32_e32 v252, v131, v252
	s_waitcnt lgkmcnt(3)
	v_mfma_f32_32x32x16_bf16 v[216:231], v[248:251], v[188:191], v[216:231]
	ds_read_b128 v[248:251], v192 offset:40960
	v_exp_f32_e32 v150, v150
	v_add_f32_e32 v252, v148, v252
	v_exp_f32_e32 v134, v134
	v_add_f32_e32 v252, v132, v252
	v_exp_f32_e32 v151, v151
	v_add_f32_e32 v252, v149, v252
	v_exp_f32_e32 v135, v135
	v_add_f32_e32 v252, v133, v252
	v_exp_f32_e32 v152, v152
	v_add_f32_e32 v252, v150, v252
	s_waitcnt lgkmcnt(3)
	v_mfma_f32_32x32x16_bf16 v[232:247], v[180:183], v[188:191], v[232:247]
	v_add_u32_e32 v253, s7, v210
	v_xor_b32_e32 v253, 0x80, v253
	ds_read_b128 v[188:191], v214 offset:128
	ds_read_b128 v[180:183], v253 offset:32768
	v_exp_f32_e32 v136, v136
	v_add_f32_e32 v252, v134, v252
	v_exp_f32_e32 v153, v153
	v_add_f32_e32 v252, v151, v252
	v_exp_f32_e32 v137, v137
	v_add_f32_e32 v252, v135, v252
	v_exp_f32_e32 v154, v154
	v_add_f32_e32 v252, v152, v252
	v_exp_f32_e32 v138, v138
	v_add_f32_e32 v252, v136, v252
	s_waitcnt lgkmcnt(3)
	v_mfma_f32_32x32x16_bf16 v[216:231], v[184:187], v[176:179], v[216:231]
	ds_read_b128 v[184:187], v253 offset:40960
	v_exp_f32_e32 v155, v155
	v_add_f32_e32 v252, v153, v252
	v_exp_f32_e32 v139, v139
	v_add_f32_e32 v252, v137, v252
	v_exp_f32_e32 v156, v156
	v_add_f32_e32 v252, v154, v252
	v_exp_f32_e32 v140, v140
	v_add_f32_e32 v252, v138, v252
	v_exp_f32_e32 v157, v157
	v_add_f32_e32 v252, v155, v252
	s_waitcnt lgkmcnt(3)
	v_mfma_f32_32x32x16_bf16 v[232:247], v[248:251], v[176:179], v[232:247]
	v_exp_f32_e32 v141, v141
	v_add_f32_e32 v252, v139, v252
	v_exp_f32_e32 v158, v158
	v_add_f32_e32 v252, v156, v252
	v_exp_f32_e32 v142, v142
	v_add_f32_e32 v252, v140, v252
	v_exp_f32_e32 v159, v159
	v_add_f32_e32 v252, v157, v252
	v_exp_f32_e32 v143, v143
	v_add_f32_e32 v252, v141, v252
	s_waitcnt lgkmcnt(1)
	v_mfma_f32_32x32x16_bf16 v[216:231], v[180:183], v[188:191], v[216:231]
	v_add_f32_e32 v252, v158, v252
	v_add_f32_e32 v252, v142, v252
	v_add_f32_e32 v252, v159, v252
	v_add_f32_e32 v252, v143, v252
	v_add_f32_e32 v198, v198, v252
	v_cvt_pk_bf16_f32 v144, v144, v145
	v_cvt_pk_bf16_f32 v145, v146, v147
	v_cvt_pk_bf16_f32 v146, v148, v149
	v_cvt_pk_bf16_f32 v147, v150, v151
	v_cvt_pk_bf16_f32 v148, v152, v153
	s_waitcnt lgkmcnt(0)
	v_mfma_f32_32x32x16_bf16 v[232:247], v[184:187], v[188:191], v[232:247]
	v_cvt_pk_bf16_f32 v149, v154, v155
	v_cvt_pk_bf16_f32 v150, v156, v157
	v_cvt_pk_bf16_f32 v151, v158, v159
	v_cvt_pk_bf16_f32 v128, v128, v129
	v_cvt_pk_bf16_f32 v129, v130, v131
	v_cvt_pk_bf16_f32 v130, v132, v133
	v_cvt_pk_bf16_f32 v131, v134, v135
	v_cvt_pk_bf16_f32 v132, v136, v137
	v_cvt_pk_bf16_f32 v133, v138, v139
	v_cvt_pk_bf16_f32 v134, v140, v141
	v_cvt_pk_bf16_f32 v135, v142, v143
	v_add_u32_e32 v192, s7, v215
	ds_read_b64_tr_b16 v[176:177], v192 offset:0
	ds_read_b64_tr_b16 v[178:179], v192 offset:0x800
	ds_read_b64_tr_b16 v[180:181], v192 offset:0x1000
	ds_read_b64_tr_b16 v[182:183], v192 offset:0x1800
	ds_read_b64_tr_b16 v[184:185], v192 offset:0x2000
	ds_read_b64_tr_b16 v[186:187], v192 offset:0x2800
	ds_read_b64_tr_b16 v[188:189], v192 offset:0x3000
	ds_read_b64_tr_b16 v[190:191], v192 offset:0x3800
	s_waitcnt lgkmcnt(6)
	v_mfma_f32_32x32x16_bf16 v[0:15], v[144:147], v[176:179], v[0:15]
	ds_read_b64_tr_b16 v[136:137], v192 offset:0x200
	ds_read_b64_tr_b16 v[138:139], v192 offset:0xa00
	v_exp_f32_e32 v216, v216
	v_exp_f32_e32 v232, v232
	v_exp_f32_e32 v217, v217
	v_exp_f32_e32 v233, v233
	v_exp_f32_e32 v218, v218
	s_waitcnt lgkmcnt(6)
	v_mfma_f32_32x32x16_bf16 v[0:15], v[148:151], v[180:183], v[0:15]
	ds_read_b64_tr_b16 v[140:141], v192 offset:0x1200
	ds_read_b64_tr_b16 v[142:143], v192 offset:0x1a00
	v_add_f32_e32 v253, 0, v216
	v_exp_f32_e32 v234, v234
	v_add_f32_e32 v253, v232, v253
	v_exp_f32_e32 v219, v219
	v_add_f32_e32 v253, v217, v253
	s_waitcnt lgkmcnt(6)
; #define SBAR() __builtin_amdgcn_sched_barrier(0)
; template <int NMAP, int D0> __device__ __forceinline__ void pv_all(f32x16 (&o)[NMAP][4], int vb, const bf16x8 (&pa)[NMAP][4]) {
;     const s16x4 l0 = tr_read<v_rd_off(D0, 0, 0)>(vb), h0 = tr_read<v_rd_off(D0, 0, 1)>(vb), l1 = tr_read<v_rd_off(D0, 1, 0)>(vb), h1 = tr_read<v_rd_off(D0, 1, 1)>(vb);
;     const s16x4 l2 = tr_read<v_rd_off(D0, 2, 0)>(vb), h2 = tr_read<v_rd_off(D0, 2, 1)>(vb), l3 = tr_read<v_rd_off(D0, 3, 0)>(vb), h3 = tr_read<v_rd_off(D0, 3, 1)>(vb);
;     asm volatile("s_waitcnt lgkmcnt(0)" ::: "memory"); SBAR();
;     ...
;     const bf16x8 v0 = PK(l0, h0), v1 = PK(l1, h1), v2 = PK(l2, h2), v3 = PK(l3, h3);
;     ...
; #pragma unroll
;     for (int mp = 0; mp < NMAP; ++mp) o[mp][D0] = __builtin_amdgcn_mfma_f32_32x32x16_bf16(pa[mp][0], v0, o[mp][D0], 0, 0, 0);
; #pragma unroll
;     for (int mp = 0; mp < NMAP; ++mp) o[mp][D0] = __builtin_amdgcn_mfma_f32_32x32x16_bf16(pa[mp][1], v1, o[mp][D0], 0, 0, 0);
; #pragma unroll
;     for (int mp = 0; mp < NMAP; ++mp) o[mp][D0] = __builtin_amdgcn_mfma_f32_32x32x16_bf16(pa[mp][2], v2, o[mp][D0], 0, 0, 0);
; #pragma unroll
;     for (int mp = 0; mp < NMAP; ++mp) o[mp][D0] = __builtin_amdgcn_mfma_f32_32x32x16_bf16(pa[mp][3], v3, o[mp][D0], 0, 0, 0);
; }
; template <int MODE, bool FAST>
; __device__ __forceinline__ int attn_item(const AttnP& a, int b, int h, int blk, char* lds) {
;     ...
;                 if (FAST) {
;                     float ps1 = 0.f;
; #pragma unroll
;                     for (int r = 0; r < 16; ++r) p0[r] = __builtin_amdgcn_exp2f(p0[r]);
; #pragma unroll
;                     for (int r = 0; r < 16; ++r) p1[r] = __builtin_amdgcn_exp2f(p1[r]);
; #pragma unroll
;                     for (int r = 0; r < 16; ++r) { ps1 += p0[r]; ps1 += p1[r]; }
;                     l_reg[mp] += ps1;
	v_mfma_f32_32x32x16_bf16 v[0:15], v[128:131], v[184:187], v[0:15]
	ds_read_b64_tr_b16 v[152:153], v192 offset:0x2200
	ds_read_b64_tr_b16 v[154:155], v192 offset:0x2a00
	v_exp_f32_e32 v235, v235
	v_add_f32_e32 v253, v233, v253
	v_exp_f32_e32 v220, v220
	v_add_f32_e32 v253, v218, v253
	v_exp_f32_e32 v236, v236
	s_waitcnt lgkmcnt(6)
	v_mfma_f32_32x32x16_bf16 v[0:15], v[132:135], v[188:191], v[0:15]
	ds_read_b64_tr_b16 v[156:157], v192 offset:0x3200
	ds_read_b64_tr_b16 v[158:159], v192 offset:0x3a00
	v_add_f32_e32 v253, v234, v253
	v_exp_f32_e32 v221, v221
	v_add_f32_e32 v253, v219, v253
	v_exp_f32_e32 v237, v237
	v_add_f32_e32 v253, v235, v253
	s_waitcnt lgkmcnt(6)
	v_mfma_f32_32x32x16_bf16 v[16:31], v[144:147], v[136:139], v[16:31]
	ds_read_b64_tr_b16 v[176:177], v192 offset:0x400
	ds_read_b64_tr_b16 v[178:179], v192 offset:0xc00
	v_exp_f32_e32 v222, v222
	v_add_f32_e32 v253, v220, v253
	v_exp_f32_e32 v238, v238
	v_add_f32_e32 v253, v236, v253
	v_exp_f32_e32 v223, v223
	s_waitcnt lgkmcnt(6)
	v_mfma_f32_32x32x16_bf16 v[16:31], v[148:151], v[140:143], v[16:31]
	ds_read_b64_tr_b16 v[180:181], v192 offset:0x1400
	ds_read_b64_tr_b16 v[182:183], v192 offset:0x1c00
	v_add_f32_e32 v253, v221, v253
	v_exp_f32_e32 v239, v239
	v_add_f32_e32 v253, v237, v253
	v_exp_f32_e32 v224, v224
	v_add_f32_e32 v253, v222, v253
	s_waitcnt lgkmcnt(6)
	v_mfma_f32_32x32x16_bf16 v[16:31], v[128:131], v[152:155], v[16:31]
	ds_read_b64_tr_b16 v[184:185], v192 offset:0x2400
	ds_read_b64_tr_b16 v[186:187], v192 offset:0x2c00
	v_exp_f32_e32 v240, v240
	v_add_f32_e32 v253, v238, v253
	v_exp_f32_e32 v225, v225
	v_add_f32_e32 v253, v223, v253
	v_exp_f32_e32 v241, v241
	s_waitcnt lgkmcnt(6)
	v_mfma_f32_32x32x16_bf16 v[16:31], v[132:135], v[156:159], v[16:31]
	ds_read_b64_tr_b16 v[188:189], v192 offset:0x3400
	ds_read_b64_tr_b16 v[190:191], v192 offset:0x3c00
	v_add_f32_e32 v253, v239, v253
	v_exp_f32_e32 v226, v226
	v_add_f32_e32 v253, v224, v253
	v_exp_f32_e32 v242, v242
	v_add_f32_e32 v253, v240, v253
	s_waitcnt lgkmcnt(6)
	v_mfma_f32_32x32x16_bf16 v[32:47], v[144:147], v[176:179], v[32:47]
	ds_read_b64_tr_b16 v[136:137], v192 offset:0x600
	ds_read_b64_tr_b16 v[138:139], v192 offset:0xe00
	v_exp_f32_e32 v227, v227
	v_add_f32_e32 v253, v225, v253
	v_exp_f32_e32 v243, v243
	v_add_f32_e32 v253, v241, v253
	v_exp_f32_e32 v228, v228
	s_waitcnt lgkmcnt(6)
	v_mfma_f32_32x32x16_bf16 v[32:47], v[148:151], v[180:183], v[32:47]
	ds_read_b64_tr_b16 v[140:141], v192 offset:0x1600
	ds_read_b64_tr_b16 v[142:143], v192 offset:0x1e00
	v_add_f32_e32 v253, v226, v253
	v_exp_f32_e32 v244, v244
	v_add_f32_e32 v253, v242, v253
	v_exp_f32_e32 v229, v229
	v_add_f32_e32 v253, v227, v253
	s_waitcnt lgkmcnt(6)
	v_mfma_f32_32x32x16_bf16 v[32:47], v[128:131], v[184:187], v[32:47]
	ds_read_b64_tr_b16 v[152:153], v192 offset:0x2600
	ds_read_b64_tr_b16 v[154:155], v192 offset:0x2e00
	v_exp_f32_e32 v245, v245
	v_add_f32_e32 v253, v243, v253
	v_exp_f32_e32 v230, v230
	v_add_f32_e32 v253, v228, v253
	v_exp_f32_e32 v246, v246
	s_waitcnt lgkmcnt(6)
	v_mfma_f32_32x32x16_bf16 v[32:47], v[132:135], v[188:191], v[32:47]
	ds_read_b64_tr_b16 v[156:157], v192 offset:0x3600
	ds_read_b64_tr_b16 v[158:159], v192 offset:0x3e00
	v_add_f32_e32 v253, v244, v253
	v_exp_f32_e32 v231, v231
	v_add_f32_e32 v253, v229, v253
	v_exp_f32_e32 v247, v247
	v_add_f32_e32 v253, v245, v253
	s_waitcnt lgkmcnt(6)
	v_mfma_f32_32x32x16_bf16 v[48:63], v[144:147], v[136:139], v[48:63]
	ds_read_b64_tr_b16 v[176:177], v192 offset:0
	ds_read_b64_tr_b16 v[178:179], v192 offset:0x800
	v_add_f32_e32 v253, v230, v253
	v_add_f32_e32 v253, v246, v253
	v_add_f32_e32 v253, v231, v253
	v_add_f32_e32 v253, v247, v253
	v_add_f32_e32 v199, v199, v253
	s_waitcnt lgkmcnt(6)
; #define SBAR() __builtin_amdgcn_sched_barrier(0)
; __device__ __forceinline__ int crow(int r, int hi) { return (r & 3) + 8 * (r >> 2) + 4 * hi; }
; template <int NMAP, int D0> __device__ __forceinline__ void pv_all(f32x16 (&o)[NMAP][4], int vb, const bf16x8 (&pa)[NMAP][4]) {
;     const s16x4 l0 = tr_read<v_rd_off(D0, 0, 0)>(vb), h0 = tr_read<v_rd_off(D0, 0, 1)>(vb), l1 = tr_read<v_rd_off(D0, 1, 0)>(vb), h1 = tr_read<v_rd_off(D0, 1, 1)>(vb);
;     const s16x4 l2 = tr_read<v_rd_off(D0, 2, 0)>(vb), h2 = tr_read<v_rd_off(D0, 2, 1)>(vb), l3 = tr_read<v_rd_off(D0, 3, 0)>(vb), h3 = tr_read<v_rd_off(D0, 3, 1)>(vb);
;     asm volatile("s_waitcnt lgkmcnt(0)" ::: "memory"); SBAR();
;     ...
;     const bf16x8 v0 = PK(l0, h0), v1 = PK(l1, h1), v2 = PK(l2, h2), v3 = PK(l3, h3);
;     ...
; #pragma unroll
;     for (int mp = 0; mp < NMAP; ++mp) o[mp][D0] = __builtin_amdgcn_mfma_f32_32x32x16_bf16(pa[mp][0], v0, o[mp][D0], 0, 0, 0);
; #pragma unroll
;     for (int mp = 0; mp < NMAP; ++mp) o[mp][D0] = __builtin_amdgcn_mfma_f32_32x32x16_bf16(pa[mp][1], v1, o[mp][D0], 0, 0, 0);
; #pragma unroll
;     for (int mp = 0; mp < NMAP; ++mp) o[mp][D0] = __builtin_amdgcn_mfma_f32_32x32x16_bf16(pa[mp][2], v2, o[mp][D0], 0, 0, 0);
; #pragma unroll
;     for (int mp = 0; mp < NMAP; ++mp) o[mp][D0] = __builtin_amdgcn_mfma_f32_32x32x16_bf16(pa[mp][3], v3, o[mp][D0], 0, 0, 0);
; }
; template <int MODE, bool FAST>
; __device__ __forceinline__ int attn_item(const AttnP& a, int b, int h, int blk, char* lds) {
;     ...
;                 PK4(p0, 0, pa[mp][0]); PK4(p0, 8, pa[mp][1]); PK4(p1, 0, pa[mp][2]); PK4(p1, 8, pa[mp][3]);
;     ...
;                 if (!FAST && __any(alpha < 1.f)) {
;                     if (hi == 0) wsf[r32] = alpha;
;                     asm volatile("s_waitcnt lgkmcnt(0)" ::: "memory");
; #pragma unroll
;                     for (int r = 0; r < 16; ++r) { const float al = wsf[crow(r, hi)];
; #pragma unroll
;                         for (int d = 0; d < 4; ++d) o[mp][d][r] *= al; }
;                 }
;             }
;             SBAR();
;             pv_all<NMAP, 0>(o, vb, pa); pv_all<NMAP, 1>(o, vb, pa); pv_all<NMAP, 2>(o, vb, pa); pv_all<NMAP, 3>(o, vb, pa);
;         }
;         asm volatile("s_waitcnt vmcnt(0)" ::: "memory");
;         __syncthreads();
	v_mfma_f32_32x32x16_bf16 v[48:63], v[148:151], v[140:143], v[48:63]
	ds_read_b64_tr_b16 v[180:181], v192 offset:0x1000
	ds_read_b64_tr_b16 v[182:183], v192 offset:0x1800
	v_cvt_pk_bf16_f32 v216, v216, v217
	v_cvt_pk_bf16_f32 v217, v218, v219
	v_cvt_pk_bf16_f32 v218, v220, v221
	v_cvt_pk_bf16_f32 v219, v222, v223
	v_cvt_pk_bf16_f32 v220, v224, v225
	s_waitcnt lgkmcnt(6)
	v_mfma_f32_32x32x16_bf16 v[48:63], v[128:131], v[152:155], v[48:63]
	ds_read_b64_tr_b16 v[184:185], v192 offset:0x2000
	ds_read_b64_tr_b16 v[186:187], v192 offset:0x2800
	v_cvt_pk_bf16_f32 v221, v226, v227
	v_cvt_pk_bf16_f32 v222, v228, v229
	v_cvt_pk_bf16_f32 v223, v230, v231
	v_cvt_pk_bf16_f32 v232, v232, v233
	v_cvt_pk_bf16_f32 v233, v234, v235
	s_waitcnt lgkmcnt(6)
	v_mfma_f32_32x32x16_bf16 v[48:63], v[132:135], v[156:159], v[48:63]
	ds_read_b64_tr_b16 v[188:189], v192 offset:0x3000
	ds_read_b64_tr_b16 v[190:191], v192 offset:0x3800
	v_cvt_pk_bf16_f32 v234, v236, v237
	v_cvt_pk_bf16_f32 v235, v238, v239
	v_cvt_pk_bf16_f32 v236, v240, v241
	v_cvt_pk_bf16_f32 v237, v242, v243
	v_cvt_pk_bf16_f32 v238, v244, v245
	v_cvt_pk_bf16_f32 v239, v246, v247
	s_waitcnt lgkmcnt(6)
	v_mfma_f32_32x32x16_bf16 v[64:79], v[216:219], v[176:179], v[64:79]
	ds_read_b64_tr_b16 v[136:137], v192 offset:0x200
	ds_read_b64_tr_b16 v[138:139], v192 offset:0xa00
	s_waitcnt lgkmcnt(6)
	v_mfma_f32_32x32x16_bf16 v[64:79], v[220:223], v[180:183], v[64:79]
	ds_read_b64_tr_b16 v[140:141], v192 offset:0x1200
	ds_read_b64_tr_b16 v[142:143], v192 offset:0x1a00
	s_waitcnt lgkmcnt(6)
	v_mfma_f32_32x32x16_bf16 v[64:79], v[232:235], v[184:187], v[64:79]
	ds_read_b64_tr_b16 v[152:153], v192 offset:0x2200
	ds_read_b64_tr_b16 v[154:155], v192 offset:0x2a00
	s_waitcnt lgkmcnt(6)
	v_mfma_f32_32x32x16_bf16 v[64:79], v[236:239], v[188:191], v[64:79]
	ds_read_b64_tr_b16 v[156:157], v192 offset:0x3200
	ds_read_b64_tr_b16 v[158:159], v192 offset:0x3a00
	s_waitcnt lgkmcnt(6)
	v_mfma_f32_32x32x16_bf16 v[80:95], v[216:219], v[136:139], v[80:95]
	ds_read_b64_tr_b16 v[176:177], v192 offset:0x400
	ds_read_b64_tr_b16 v[178:179], v192 offset:0xc00
	s_waitcnt lgkmcnt(6)
	v_mfma_f32_32x32x16_bf16 v[80:95], v[220:223], v[140:143], v[80:95]
	ds_read_b64_tr_b16 v[180:181], v192 offset:0x1400
	ds_read_b64_tr_b16 v[182:183], v192 offset:0x1c00
	s_waitcnt lgkmcnt(6)
	v_mfma_f32_32x32x16_bf16 v[80:95], v[232:235], v[152:155], v[80:95]
	ds_read_b64_tr_b16 v[184:185], v192 offset:0x2400
	ds_read_b64_tr_b16 v[186:187], v192 offset:0x2c00
	s_waitcnt lgkmcnt(6)
	v_mfma_f32_32x32x16_bf16 v[80:95], v[236:239], v[156:159], v[80:95]
	ds_read_b64_tr_b16 v[188:189], v192 offset:0x3400
	ds_read_b64_tr_b16 v[190:191], v192 offset:0x3c00
	s_waitcnt lgkmcnt(6)
	v_mfma_f32_32x32x16_bf16 v[96:111], v[216:219], v[176:179], v[96:111]
	ds_read_b64_tr_b16 v[136:137], v192 offset:0x600
	ds_read_b64_tr_b16 v[138:139], v192 offset:0xe00
	s_waitcnt lgkmcnt(6)
	v_mfma_f32_32x32x16_bf16 v[96:111], v[220:223], v[180:183], v[96:111]
	ds_read_b64_tr_b16 v[140:141], v192 offset:0x1600
	ds_read_b64_tr_b16 v[142:143], v192 offset:0x1e00
	s_waitcnt lgkmcnt(6)
	v_mfma_f32_32x32x16_bf16 v[96:111], v[232:235], v[184:187], v[96:111]
	ds_read_b64_tr_b16 v[152:153], v192 offset:0x2600
	ds_read_b64_tr_b16 v[154:155], v192 offset:0x2e00
	s_waitcnt lgkmcnt(6)
	v_mfma_f32_32x32x16_bf16 v[96:111], v[236:239], v[188:191], v[96:111]
	ds_read_b64_tr_b16 v[156:157], v192 offset:0x3600
	ds_read_b64_tr_b16 v[158:159], v192 offset:0x3e00
	s_add_u32 s4, s4, 0x4000
	s_addc_u32 s5, s5, 0
	s_cmp_lg_u32 s4, 0x210000
	s_waitcnt vmcnt(0) lgkmcnt(0)
	s_barrier
	s_cbranch_scc1 .Lmy_top
	v_mfma_f32_32x32x16_bf16 v[112:127], v[216:219], v[136:139], v[112:127]
	v_mfma_f32_32x32x16_bf16 v[112:127], v[220:223], v[140:143], v[112:127]
	v_mfma_f32_32x32x16_bf16 v[112:127], v[232:235], v[152:155], v[112:127]
	v_mfma_f32_32x32x16_bf16 v[112:127], v[236:239], v[156:159], v[112:127]
